# HGRN state scan loop: 10-chunk units with the next unit's loads in flight (counted vmcnt) instead of partially serialised 26-chunk batches
# baseline (speedup 1.0000x reference)
; DI int ltid() { int t = threadIdx.x & 255; asm volatile("" : "+v"(t)); return t; }
; DI void scan_item(const Params& p, int it) {
;   const int chain = it >> 4, e = (it & 15) * 256 + ltid(), k = e >> 6;
;   float* L = p.HL + (size_t)chain * NCHUNK * 4096 + e;
;   const float* dc = p.Hdec + chain * NCHUNK * 64 + k;
;   float S = 0.f;
;   for (int n0 = 0; n0 < NCHUNK; n0 += 26) {
;     float l[26], dd[26];
; #pragma unroll
;     for (int j = 0; j < 26; ++j) { l[j] = L[(size_t)(n0 + j) * 4096]; dd[j] = dc[(n0 + j) * 64]; }
; #pragma unroll
;     for (int j = 0; j < 26; ++j) { L[(size_t)(n0 + j) * 4096] = S; S = dd[j] * S + l[j]; }
.LBB0_432:
	s_andn2_b64 vcc, exec, s[2:3]
	s_cbranch_vccnz .LBB0_321
	s_ashr_i32 s2, s40, 4
	s_lshl_b32 s3, s40, 8
	s_and_b32 s3, s3, 0xf00
	v_mov_b32_e32 v2, v212
	s_mul_hi_i32 s24, s2, 0x410000
	s_mul_i32 s25, s2, 0x410000
	s_mulk_i32 s2, 0x4100
	s_and_b32 s22, s39, 0xf00
	v_add_u32_e32 v0, s3, v2
	s_ashr_i32 s3, s2, 31
	s_lshl_b64 s[2:3], s[2:3], 2
	v_readlane_b32 s26, v253, 52
	v_ashrrev_i32_e32 v0, 6, v0
	s_add_u32 s2, s26, s2
	v_readlane_b32 s26, v253, 53
	v_ashrrev_i32_e32 v1, 31, v0
	s_addc_u32 s3, s26, s3
	v_lshl_add_u64 v[0:1], v[0:1], 2, s[2:3]
	v_readlane_b32 s2, v253, 54
	v_add_u32_e32 v2, s22, v2
	s_add_u32 s2, s2, s25
	v_readlane_b32 s3, v253, 55
	v_ashrrev_i32_e32 v3, 31, v2
	s_addc_u32 s3, s3, s24
	v_lshl_add_u64 v[2:3], v[2:3], 2, s[2:3]
	v_mov_b32_e32 v18, 0
	s_movk_i32 s2, 0xffe6
	s_mov_b32 s24, 0x4000
	s_mov_b32 s25, 0
	s_mov_b32 s100, 0xa00
	s_mov_b32 s101, 0
	v_add_co_u32_e32 v4, vcc, 0xfff9c000, v2
	s_nop 1
	v_addc_co_u32_e32 v5, vcc, -1, v3, vcc
	v_add_co_u32_e32 v8, vcc, 0xffffe700, v0
	s_nop 1
	v_addc_co_u32_e32 v9, vcc, -1, v1, vcc
	v_mov_b32_e32 v6, v4
	v_mov_b32_e32 v7, v5
	s_mov_b32 s2, 0
	global_load_dword v20, v[4:5], off
	v_lshl_add_u64 v[4:5], v[4:5], 0, s[24:25]
	global_load_dword v30, v[8:9], off
	global_load_dword v21, v[4:5], off
	v_lshl_add_u64 v[4:5], v[4:5], 0, s[24:25]
	global_load_dword v31, v[8:9], off offset:256
	global_load_dword v22, v[4:5], off
	v_lshl_add_u64 v[4:5], v[4:5], 0, s[24:25]
	global_load_dword v32, v[8:9], off offset:512
	global_load_dword v23, v[4:5], off
	v_lshl_add_u64 v[4:5], v[4:5], 0, s[24:25]
	global_load_dword v33, v[8:9], off offset:768
	global_load_dword v24, v[4:5], off
	v_lshl_add_u64 v[4:5], v[4:5], 0, s[24:25]
	global_load_dword v34, v[8:9], off offset:1024
	global_load_dword v25, v[4:5], off
	v_lshl_add_u64 v[4:5], v[4:5], 0, s[24:25]
	global_load_dword v35, v[8:9], off offset:1280
	global_load_dword v26, v[4:5], off
	v_lshl_add_u64 v[4:5], v[4:5], 0, s[24:25]
	global_load_dword v36, v[8:9], off offset:1536
	global_load_dword v27, v[4:5], off
	v_lshl_add_u64 v[4:5], v[4:5], 0, s[24:25]
	global_load_dword v37, v[8:9], off offset:1792
	global_load_dword v28, v[4:5], off
	v_lshl_add_u64 v[4:5], v[4:5], 0, s[24:25]
	global_load_dword v38, v[8:9], off offset:2048
	global_load_dword v29, v[4:5], off
	v_lshl_add_u64 v[4:5], v[4:5], 0, s[24:25]
	global_load_dword v39, v[8:9], off offset:2304
	v_lshl_add_u64 v[8:9], v[8:9], 0, s[100:101]
; DI void scan_item(const Params& p, int it) {
;     ...
;   for (int n0 = 0; n0 < NCHUNK; n0 += 26) {
;     float l[26], dd[26];
; #pragma unroll
;     for (int j = 0; j < 26; ++j) { l[j] = L[(size_t)(n0 + j) * 4096]; dd[j] = dc[(n0 + j) * 64]; }
; #pragma unroll
;     for (int j = 0; j < 26; ++j) { L[(size_t)(n0 + j) * 4096] = S; S = dd[j] * S + l[j]; }
;   }
.LBB0_434:
	global_load_dword v40, v[4:5], off
	v_lshl_add_u64 v[4:5], v[4:5], 0, s[24:25]
	global_load_dword v50, v[8:9], off
	global_load_dword v41, v[4:5], off
	v_lshl_add_u64 v[4:5], v[4:5], 0, s[24:25]
	global_load_dword v51, v[8:9], off offset:256
	global_load_dword v42, v[4:5], off
	v_lshl_add_u64 v[4:5], v[4:5], 0, s[24:25]
	global_load_dword v52, v[8:9], off offset:512
	global_load_dword v43, v[4:5], off
	v_lshl_add_u64 v[4:5], v[4:5], 0, s[24:25]
	global_load_dword v53, v[8:9], off offset:768
	global_load_dword v44, v[4:5], off
	v_lshl_add_u64 v[4:5], v[4:5], 0, s[24:25]
	global_load_dword v54, v[8:9], off offset:1024
	global_load_dword v45, v[4:5], off
	v_lshl_add_u64 v[4:5], v[4:5], 0, s[24:25]
	global_load_dword v55, v[8:9], off offset:1280
	global_load_dword v46, v[4:5], off
	v_lshl_add_u64 v[4:5], v[4:5], 0, s[24:25]
	global_load_dword v56, v[8:9], off offset:1536
	global_load_dword v47, v[4:5], off
	v_lshl_add_u64 v[4:5], v[4:5], 0, s[24:25]
	global_load_dword v57, v[8:9], off offset:1792
	global_load_dword v48, v[4:5], off
	v_lshl_add_u64 v[4:5], v[4:5], 0, s[24:25]
	global_load_dword v58, v[8:9], off offset:2048
	global_load_dword v49, v[4:5], off
	v_lshl_add_u64 v[4:5], v[4:5], 0, s[24:25]
	global_load_dword v59, v[8:9], off offset:2304
	v_lshl_add_u64 v[8:9], v[8:9], 0, s[100:101]
	s_waitcnt vmcnt(38)
	global_store_dword v[6:7], v18, off
	v_fmac_f32_e32 v20, v18, v30
	v_lshl_add_u64 v[6:7], v[6:7], 0, s[24:25]
	s_waitcnt vmcnt(37)
	global_store_dword v[6:7], v20, off
	v_fmac_f32_e32 v21, v20, v31
	v_lshl_add_u64 v[6:7], v[6:7], 0, s[24:25]
	s_waitcnt vmcnt(36)
	global_store_dword v[6:7], v21, off
	v_fmac_f32_e32 v22, v21, v32
	v_lshl_add_u64 v[6:7], v[6:7], 0, s[24:25]
	s_waitcnt vmcnt(35)
	global_store_dword v[6:7], v22, off
	v_fmac_f32_e32 v23, v22, v33
	v_lshl_add_u64 v[6:7], v[6:7], 0, s[24:25]
	s_waitcnt vmcnt(34)
	global_store_dword v[6:7], v23, off
	v_fmac_f32_e32 v24, v23, v34
	v_lshl_add_u64 v[6:7], v[6:7], 0, s[24:25]
	s_waitcnt vmcnt(33)
	global_store_dword v[6:7], v24, off
	v_fmac_f32_e32 v25, v24, v35
	v_lshl_add_u64 v[6:7], v[6:7], 0, s[24:25]
	s_waitcnt vmcnt(32)
	global_store_dword v[6:7], v25, off
	v_fmac_f32_e32 v26, v25, v36
	v_lshl_add_u64 v[6:7], v[6:7], 0, s[24:25]
	s_waitcnt vmcnt(31)
	global_store_dword v[6:7], v26, off
	v_fmac_f32_e32 v27, v26, v37
	v_lshl_add_u64 v[6:7], v[6:7], 0, s[24:25]
	s_waitcnt vmcnt(30)
	global_store_dword v[6:7], v27, off
	v_fmac_f32_e32 v28, v27, v38
	v_lshl_add_u64 v[6:7], v[6:7], 0, s[24:25]
	s_waitcnt vmcnt(29)
	global_store_dword v[6:7], v28, off
	v_fmac_f32_e32 v29, v28, v39
	v_lshl_add_u64 v[6:7], v[6:7], 0, s[24:25]
	v_mov_b32_e32 v18, v29
	global_load_dword v20, v[4:5], off
	v_lshl_add_u64 v[4:5], v[4:5], 0, s[24:25]
	global_load_dword v30, v[8:9], off
	global_load_dword v21, v[4:5], off
	v_lshl_add_u64 v[4:5], v[4:5], 0, s[24:25]
	global_load_dword v31, v[8:9], off offset:256
	global_load_dword v22, v[4:5], off
	v_lshl_add_u64 v[4:5], v[4:5], 0, s[24:25]
	global_load_dword v32, v[8:9], off offset:512
	global_load_dword v23, v[4:5], off
	v_lshl_add_u64 v[4:5], v[4:5], 0, s[24:25]
	global_load_dword v33, v[8:9], off offset:768
	global_load_dword v24, v[4:5], off
	v_lshl_add_u64 v[4:5], v[4:5], 0, s[24:25]
	global_load_dword v34, v[8:9], off offset:1024
	global_load_dword v25, v[4:5], off
	v_lshl_add_u64 v[4:5], v[4:5], 0, s[24:25]
	global_load_dword v35, v[8:9], off offset:1280
	global_load_dword v26, v[4:5], off
	v_lshl_add_u64 v[4:5], v[4:5], 0, s[24:25]
	global_load_dword v36, v[8:9], off offset:1536
	global_load_dword v27, v[4:5], off
	v_lshl_add_u64 v[4:5], v[4:5], 0, s[24:25]
	global_load_dword v37, v[8:9], off offset:1792
	global_load_dword v28, v[4:5], off
	v_lshl_add_u64 v[4:5], v[4:5], 0, s[24:25]
	global_load_dword v38, v[8:9], off offset:2048
	global_load_dword v29, v[4:5], off
	v_lshl_add_u64 v[4:5], v[4:5], 0, s[24:25]
	global_load_dword v39, v[8:9], off offset:2304
	v_lshl_add_u64 v[8:9], v[8:9], 0, s[100:101]
	s_waitcnt vmcnt(48)
	global_store_dword v[6:7], v18, off
	v_fmac_f32_e32 v40, v18, v50
	v_lshl_add_u64 v[6:7], v[6:7], 0, s[24:25]
	s_waitcnt vmcnt(47)
	global_store_dword v[6:7], v40, off
	v_fmac_f32_e32 v41, v40, v51
	v_lshl_add_u64 v[6:7], v[6:7], 0, s[24:25]
	s_waitcnt vmcnt(46)
	global_store_dword v[6:7], v41, off
	v_fmac_f32_e32 v42, v41, v52
	v_lshl_add_u64 v[6:7], v[6:7], 0, s[24:25]
	s_waitcnt vmcnt(45)
	global_store_dword v[6:7], v42, off
	v_fmac_f32_e32 v43, v42, v53
	v_lshl_add_u64 v[6:7], v[6:7], 0, s[24:25]
	s_waitcnt vmcnt(44)
	global_store_dword v[6:7], v43, off
	v_fmac_f32_e32 v44, v43, v54
	v_lshl_add_u64 v[6:7], v[6:7], 0, s[24:25]
	s_waitcnt vmcnt(43)
	global_store_dword v[6:7], v44, off
	v_fmac_f32_e32 v45, v44, v55
	v_lshl_add_u64 v[6:7], v[6:7], 0, s[24:25]
	s_waitcnt vmcnt(42)
	global_store_dword v[6:7], v45, off
	v_fmac_f32_e32 v46, v45, v56
	v_lshl_add_u64 v[6:7], v[6:7], 0, s[24:25]
	s_waitcnt vmcnt(41)
	global_store_dword v[6:7], v46, off
	v_fmac_f32_e32 v47, v46, v57
	v_lshl_add_u64 v[6:7], v[6:7], 0, s[24:25]
	s_waitcnt vmcnt(40)
	global_store_dword v[6:7], v47, off
	v_fmac_f32_e32 v48, v47, v58
	v_lshl_add_u64 v[6:7], v[6:7], 0, s[24:25]
	s_waitcnt vmcnt(39)
	global_store_dword v[6:7], v48, off
	v_fmac_f32_e32 v49, v48, v59
	v_lshl_add_u64 v[6:7], v[6:7], 0, s[24:25]
	v_mov_b32_e32 v18, v49
	s_add_i32 s2, s2, 1
	s_cmp_lt_u32 s2, 13
	s_cbranch_scc1 .LBB0_434
	s_waitcnt vmcnt(0)
	s_branch .LBB0_321
